# speedup vs baseline: 1.0100x; 1.0027x over previous
.LBB0_865:
	s_or_b64 exec, exec, s[48:49]
	v_add_u32_e32 v20, v31, v140
	s_waitcnt lgkmcnt(0)
	s_barrier
	ds_read_b128 v[12:15], v161
	ds_read_b128 v[8:11], v161 offset:64
	ds_read_b128 v[16:19], v20
	ds_read_b128 v[20:23], v20 offset:64
	ds_read_b128 v[228:231], v162
	ds_read_b128 v[232:235], v162 offset:64
	s_waitcnt lgkmcnt(3)
	v_mfma_f32_16x16x32_bf16 v[16:19], v[12:15], v[16:19], 0
	s_lshl_b32 s62, s74, 5
	s_sub_i32 s34, s81, s62
	s_min_i32 s75, s34, 32
	s_waitcnt lgkmcnt(2)
	v_mfma_f32_16x16x32_bf16 v[16:19], v[8:11], v[20:23], v[16:19]
	s_nop 7
	v_cndmask_b32_e64 v16, 0, v16, s[84:85]
	s_and_saveexec_b64 s[34:35], s[0:1]
	s_xor_b64 s[34:35], exec, s[34:35]
	v_cvt_pk_bf16_f32 v16, v16, s0
	ds_write_b16 v187, v16
	s_andn2_saveexec_b64 s[34:35], s[34:35]
	ds_write_b32 v188, v16 offset:35328
	s_or_b64 exec, exec, s[34:35]
	v_cndmask_b32_e64 v16, v17, 0, s[44:45]
	s_and_saveexec_b64 s[34:35], s[0:1]
	s_xor_b64 s[34:35], exec, s[34:35]
	v_cvt_pk_bf16_f32 v16, v16, s0
	ds_write_b16 v187, v16 offset:80
	s_andn2_saveexec_b64 s[34:35], s[34:35]
	ds_write_b32 v189, v16 offset:35328
	s_or_b64 exec, exec, s[34:35]
	v_cndmask_b32_e64 v16, 0, v18, s[86:87]
	s_and_saveexec_b64 s[34:35], s[0:1]
	s_xor_b64 s[34:35], exec, s[34:35]
	v_cvt_pk_bf16_f32 v16, v16, s0
	ds_write_b16 v187, v16 offset:160
	s_andn2_saveexec_b64 s[34:35], s[34:35]
	ds_write_b32 v190, v16 offset:35328
	s_or_b64 exec, exec, s[34:35]
	v_cndmask_b32_e64 v16, 0, v19, s[4:5]
	s_and_saveexec_b64 s[34:35], s[0:1]
	s_xor_b64 s[34:35], exec, s[34:35]
	v_cvt_pk_bf16_f32 v16, v16, s0
	ds_write_b16 v187, v16 offset:240
	s_andn2_saveexec_b64 s[34:35], s[34:35]
	ds_write_b32 v191, v16 offset:35328
	s_or_b64 exec, exec, s[34:35]
	s_waitcnt lgkmcnt(0)
	v_mfma_f32_16x16x32_bf16 v[12:15], v[12:15], v[228:231], 0
	s_waitcnt lgkmcnt(0)
	v_mfma_f32_16x16x32_bf16 v[8:11], v[8:11], v[232:235], v[12:15]
	s_nop 7
	v_cndmask_b32_e64 v8, 0, v8, s[24:25]
	s_and_saveexec_b64 s[34:35], s[0:1]
	s_xor_b64 s[34:35], exec, s[34:35]
	v_cvt_pk_bf16_f32 v8, v8, s0
	ds_write_b16 v192, v8
	s_andn2_saveexec_b64 s[34:35], s[34:35]
	ds_write_b32 v188, v8 offset:35392
	s_or_b64 exec, exec, s[34:35]
	v_cndmask_b32_e64 v8, v9, 0, s[26:27]
	s_and_saveexec_b64 s[34:35], s[0:1]
	s_xor_b64 s[34:35], exec, s[34:35]
	v_cvt_pk_bf16_f32 v8, v8, s0
	ds_write_b16 v192, v8 offset:80
	s_andn2_saveexec_b64 s[34:35], s[34:35]
	ds_write_b32 v189, v8 offset:35392
	s_or_b64 exec, exec, s[34:35]
	v_cndmask_b32_e64 v8, 0, v10, s[28:29]
	s_and_saveexec_b64 s[34:35], s[0:1]
	s_xor_b64 s[34:35], exec, s[34:35]
	v_cvt_pk_bf16_f32 v8, v8, s0
	ds_write_b16 v192, v8 offset:160
	s_andn2_saveexec_b64 s[34:35], s[34:35]
	ds_write_b32 v190, v8 offset:35392
	s_or_b64 exec, exec, s[34:35]
	v_cndmask_b32_e64 v8, 0, v11, s[30:31]
	s_and_saveexec_b64 s[34:35], s[0:1]
	s_xor_b64 s[34:35], exec, s[34:35]
	v_cvt_pk_bf16_f32 v8, v8, s0
	ds_write_b16 v192, v8 offset:240
	s_andn2_saveexec_b64 s[34:35], s[34:35]
	ds_write_b32 v191, v8 offset:35392
	s_or_b64 exec, exec, s[34:35]
	s_waitcnt lgkmcnt(0)
	s_barrier
	ds_read_b128 v[16:19], v163
	ds_read_b128 v[8:11], v163 offset:64
	ds_read_b128 v[12:15], v165
	s_bitcmp0_b32 s74, 0
	s_cselect_b64 s[48:49], -1, 0
	ds_read_b128 v[20:23], v165 offset:64
	ds_read_b128 v[228:231], v166
	ds_read_b128 v[232:235], v166 offset:64
	s_and_b64 s[34:35], s[48:49], exec
	s_waitcnt lgkmcnt(3)
	v_mfma_f32_16x16x32_bf16 v[12:15], v[16:19], v[12:15], 0
	s_cselect_b32 s63, 0x12800, s80
	v_or_b32_e32 v29, s63, v140
	v_add_u32_e32 v36, v29, v149
	ds_read_b128 v[210:213], v36
	v_add_u32_e32 v240, v29, v150
	ds_read_b128 v[236:239], v240
	s_waitcnt lgkmcnt(4)
	v_mfma_f32_16x16x32_bf16 v[12:15], v[8:11], v[20:23], v[12:15]
	ds_read_b128 v[20:23], v164
	s_waitcnt lgkmcnt(0)
	v_mfma_f32_16x16x32_bf16 v[12:15], v[20:23], v[210:213], v[12:15]
	s_and_saveexec_b64 s[34:35], s[6:7]
	s_cbranch_execz .LBB0_899
	s_nop 5
	ds_write_b32 v193, v12 offset:27136
	ds_write_b32 v194, v13 offset:27136
	ds_write_b32 v195, v14 offset:27136
	ds_write_b32 v196, v15 offset:27136
.LBB0_899:
	s_or_b64 exec, exec, s[34:35]
	v_add_u32_e32 v29, v29, v150
	s_waitcnt lgkmcnt(0)
	v_mfma_f32_16x16x32_bf16 v[16:19], v[16:19], v[228:231], 0
	s_waitcnt lgkmcnt(0)
	v_mfma_f32_16x16x32_bf16 v[8:11], v[8:11], v[232:235], v[16:19]
	s_nop 4
	s_waitcnt lgkmcnt(0)
	v_mfma_f32_16x16x32_bf16 v[8:11], v[20:23], v[236:239], v[8:11]
	s_and_saveexec_b64 s[34:35], s[6:7]
	s_cbranch_execz .LBB0_901
	s_nop 5
	ds_write_b32 v193, v8 offset:27200
	ds_write_b32 v194, v9 offset:27200
	ds_write_b32 v195, v10 offset:27200
	ds_write_b32 v196, v11 offset:27200
